# ROW_P1 layers>0: MIX row loads issued with the X row loads (one round trip per row instead of two)
# baseline (speedup 1.0000x reference)
; __device__ __forceinline__ unsigned pk2(float lo, float hi) { f32x2c v = {lo, hi}; return __builtin_bit_cast(unsigned, __builtin_convertvector(v, bf16x2c)); }
; __device__ __forceinline__ void row_post1(const Params& p, int layer) {
;     ...
;         xrow_load(X, layer == 0, m, lane, x);
;         row_load_bf16(MIX + (size_t)m * D, lane, mx);
;         const float rs = row_rstd(mx);
; #pragma unroll
;         for (int j = 0; j < 8; ++j) { const f32x4 g = *(const f32x4*)(g1 + 256 * j + 4 * lane); x[j] += mx[j] * rs * g; u32x2 w; w.x = pk2(x[j][0], x[j][1]); w.y = pk2(x[j][2], x[j][3]); *(u32x2*)(X + (size_t)m * D + 256 * j + 4 * lane) = w; }
;         const float rs2 = row_rstd(x);
.Lp1_mixed:
	s_add_i32 s13, s13, 1
	s_add_i32 s4, s4, s5
	s_cmp_eq_u32 s13, 1
	s_waitcnt vmcnt(7)
	v_and_b32_e32 v97, 0xffff0000, v38
	v_and_b32_e32 v99, 0xffff0000, v39
	v_lshlrev_b32_e32 v96, 16, v38
	v_lshlrev_b32_e32 v98, 16, v39
	s_waitcnt vmcnt(0)
	v_lshlrev_b32_e32 v69, 16, v36
	v_and_b32_e32 v67, 0xffff0000, v36
	v_mul_f32_e32 v36, v99, v99
	v_and_b32_e32 v93, 0xffff0000, v77
	v_and_b32_e32 v92, 0xffff0000, v76
	v_mul_f32_e32 v66, v97, v97
	v_lshlrev_b32_e32 v75, 16, v64
	v_and_b32_e32 v73, 0xffff0000, v64
	v_lshlrev_b32_e32 v70, 16, v65
	v_and_b32_e32 v71, 0xffff0000, v65
	v_lshlrev_b32_e32 v64, 16, v37
	v_and_b32_e32 v65, 0xffff0000, v37
	v_pk_fma_f32 v[36:37], v[98:99], v[98:99], v[36:37] op_sel_hi:[1,1,0]
	v_lshlrev_b32_e32 v95, 16, v77
	v_lshlrev_b32_e32 v94, 16, v76
	v_pk_mul_f32 v[38:39], v[92:93], v[92:93]
	v_pk_fma_f32 v[76:77], v[96:97], v[96:97], v[66:67] op_sel_hi:[1,1,0]
	v_pk_fma_f32 v[38:39], v[94:95], v[94:95], v[38:39]
	v_lshlrev_b32_e32 v88, 16, v78
	v_and_b32_e32 v89, 0xffff0000, v78
	v_lshlrev_b32_e32 v90, 16, v79
	v_and_b32_e32 v91, 0xffff0000, v79
	v_mov_b32_e32 v74, v76
	v_mov_b32_e32 v78, v36
	v_mov_b32_e32 v79, v75
	v_mul_f32_e32 v68, v73, v73
	v_pk_add_f32 v[36:37], v[76:77], v[36:37]
	v_pk_mul_f32 v[76:77], v[74:75], v[78:79]
	v_pk_add_f32 v[38:39], v[38:39], v[38:39] op_sel:[0,1] op_sel_hi:[1,0]
	v_mov_b32_e32 v37, v77
	v_mov_b32_e32 v39, v68
	v_pk_add_f32 v[36:37], v[36:37], v[38:39]
	v_mul_f32_e32 v38, v89, v89
	v_mul_f32_e32 v66, v91, v91
	v_mul_f32_e32 v72, v70, v70
	v_mul_f32_e32 v82, v71, v71
	v_pk_fma_f32 v[38:39], v[88:89], v[88:89], v[38:39] op_sel_hi:[1,1,0]
	v_pk_fma_f32 v[76:77], v[90:91], v[90:91], v[66:67] op_sel_hi:[1,1,0]
	v_mov_b32_e32 v39, v72
	v_mov_b32_e32 v77, v82
	v_pk_add_f32 v[38:39], v[38:39], v[76:77]
	v_and_b32_e32 v85, 0xffff0000, v81
	v_and_b32_e32 v84, 0xffff0000, v80
	v_pk_add_f32 v[36:37], v[36:37], v[38:39]
	v_lshlrev_b32_e32 v87, 16, v81
	v_lshlrev_b32_e32 v86, 16, v80
	v_pk_mul_f32 v[38:39], v[84:85], v[84:85]
	v_and_b32_e32 v81, 0xffff0000, v101
	v_pk_fma_f32 v[38:39], v[86:87], v[86:87], v[38:39]
	v_and_b32_e32 v80, 0xffff0000, v100
	v_pk_add_f32 v[38:39], v[38:39], v[38:39] op_sel:[0,1] op_sel_hi:[1,0]
	v_lshlrev_b32_e32 v83, 16, v101
	v_lshlrev_b32_e32 v82, 16, v100
	v_pk_mul_f32 v[76:77], v[80:81], v[80:81]
	v_pk_add_f32 v[36:37], v[36:37], v[36:37] op_sel:[0,1] op_sel_hi:[1,0]
	v_pk_fma_f32 v[100:101], v[82:83], v[82:83], v[76:77]
	v_lshlrev_b32_e32 v76, 16, v102
	v_and_b32_e32 v77, 0xffff0000, v102
	v_lshlrev_b32_e32 v78, 16, v103
	v_and_b32_e32 v79, 0xffff0000, v103
	v_mov_b32_e32 v68, v36
	v_mov_b32_e32 v102, v38
	v_mov_b32_e32 v103, v69
	v_pk_add_f32 v[36:37], v[36:37], v[38:39]
	v_pk_mul_f32 v[38:39], v[68:69], v[102:103]
	v_mul_f32_e32 v66, v67, v67
	v_mov_b32_e32 v37, v39
	v_pk_add_f32 v[38:39], v[100:101], v[100:101] op_sel:[0,1] op_sel_hi:[1,0]
	v_mul_f32_e32 v72, v64, v64
	v_mov_b32_e32 v39, v66
	v_pk_add_f32 v[36:37], v[36:37], v[38:39]
	v_mul_f32_e32 v38, v77, v77
	v_mul_f32_e32 v66, v79, v79
	v_mul_f32_e32 v74, v65, v65
	v_pk_fma_f32 v[38:39], v[76:77], v[76:77], v[38:39] op_sel_hi:[1,1,0]
	v_pk_fma_f32 v[100:101], v[78:79], v[78:79], v[66:67] op_sel_hi:[1,1,0]
	v_mov_b32_e32 v39, v72
	v_mov_b32_e32 v101, v74
	v_pk_add_f32 v[38:39], v[38:39], v[100:101]
	v_lshl_add_u64 v[100:101], v[0:1], 0, s[6:7]
	v_pk_add_f32 v[36:37], v[36:37], v[38:39]
	v_xor_b32_e32 v38, 1, v152
	v_add_f32_e32 v36, v36, v37
	v_mov_b32_e32 v72, v75
	v_mov_b32_e32 v66, v69
	s_waitcnt lgkmcnt(0)
	s_nop 1
	v_add_f32_dpp v36, v36, v36 quad_perm:[1,0,3,2] row_mask:0xf bank_mask:0xf bound_ctrl:1
	s_nop 1
	v_add_f32_dpp v36, v36, v36 quad_perm:[2,3,0,1] row_mask:0xf bank_mask:0xf bound_ctrl:1
	s_nop 1
	v_add_f32_dpp v36, v36, v36 row_half_mirror row_mask:0xf bank_mask:0xf bound_ctrl:1
	s_nop 1
	v_add_f32_dpp v36, v36, v36 row_mirror row_mask:0xf bank_mask:0xf bound_ctrl:1
	s_nop 1
	v_add_f32_dpp v36, v36, v36 row_bcast:15 row_mask:0xa bank_mask:0xf
	s_nop 1
	v_add_f32_dpp v36, v36, v36 row_bcast:31 row_mask:0xc bank_mask:0xf
	s_nop 1
	v_readlane_b32 vcc_lo, v36, 63
	s_nop 2
	v_mov_b32_e32 v36, vcc_lo
	v_fmamk_f32 v36, v36, 0x3a000000, v147
	v_cmp_gt_f32_e32 vcc, s29, v36
	v_mul_f32_e32 v37, 0x4b800000, v36
	s_nop 0
	v_cndmask_b32_e32 v36, v36, v37, vcc
	v_rsq_f32_e32 v36, v36
	s_nop 0
	v_mul_f32_e32 v37, 0x45800000, v36
	v_cndmask_b32_e32 v68, v36, v37, vcc
	v_pk_mul_f32 v[96:97], v[68:69], v[96:97] op_sel_hi:[0,1]
	v_pk_mul_f32 v[98:99], v[68:69], v[98:99] op_sel_hi:[0,1]
	v_pk_mul_f32 v[88:89], v[68:69], v[88:89] op_sel_hi:[0,1]
	v_pk_mul_f32 v[90:91], v[68:69], v[90:91] op_sel_hi:[0,1]
	v_pk_mul_f32 v[72:73], v[68:69], v[72:73] op_sel_hi:[0,1]
	v_pk_mul_f32 v[70:71], v[68:69], v[70:71] op_sel_hi:[0,1]
	v_pk_mul_f32 v[66:67], v[68:69], v[66:67] op_sel_hi:[0,1]
	v_pk_mul_f32 v[64:65], v[68:69], v[64:65] op_sel_hi:[0,1]
	v_pk_fma_f32 v[34:35], v[162:163], v[98:99], v[34:35]
	v_pk_fma_f32 v[32:33], v[160:161], v[96:97], v[32:33]
	v_cvt_pk_bf16_f32 v37, v34, v35
	v_cvt_pk_bf16_f32 v36, v32, v33
	global_store_dwordx2 v[100:101], v[36:37], off
	v_mov_b32_e32 v96, v94
	v_mov_b32_e32 v97, v92
	v_mov_b32_e32 v92, v95
	v_pk_mul_f32 v[96:97], v[68:69], v[96:97] op_sel_hi:[0,1]
	v_pk_mul_f32 v[92:93], v[68:69], v[92:93] op_sel_hi:[0,1]
	v_pk_fma_f32 v[30:31], v[166:167], v[92:93], v[30:31]
	v_pk_fma_f32 v[28:29], v[164:165], v[96:97], v[28:29]
	v_cvt_pk_bf16_f32 v37, v30, v31
	v_cvt_pk_bf16_f32 v36, v28, v29
	global_store_dwordx2 v[100:101], v[36:37], off offset:512
	v_pk_fma_f32 v[26:27], v[170:171], v[90:91], v[26:27]
	v_pk_fma_f32 v[24:25], v[168:169], v[88:89], v[24:25]
	v_cvt_pk_bf16_f32 v37, v26, v27
; __device__ __forceinline__ unsigned pk2(float lo, float hi) { f32x2c v = {lo, hi}; return __builtin_bit_cast(unsigned, __builtin_convertvector(v, bf16x2c)); }
; __device__ __forceinline__ void row_post1(const Params& p, int layer) {
;     ...
;         for (int j = 0; j < 8; ++j) { const f32x4 g = *(const f32x4*)(g1 + 256 * j + 4 * lane); x[j] += mx[j] * rs * g; u32x2 w; w.x = pk2(x[j][0], x[j][1]); w.y = pk2(x[j][2], x[j][3]); *(u32x2*)(X + (size_t)m * D + 256 * j + 4 * lane) = w; }
;         const float rs2 = row_rstd(x);
	v_cvt_pk_bf16_f32 v36, v24, v25
	global_store_dwordx2 v[100:101], v[36:37], off offset:1024
	v_pk_fma_f32 v[22:23], v[174:175], v[70:71], v[22:23]
	v_pk_fma_f32 v[20:21], v[172:173], v[72:73], v[20:21]
	v_cvt_pk_bf16_f32 v37, v22, v23
	v_cvt_pk_bf16_f32 v36, v20, v21
	global_store_dwordx2 v[100:101], v[36:37], off offset:1536
	v_mov_b32_e32 v70, v86
	v_mov_b32_e32 v71, v84
	v_mov_b32_e32 v84, v87
	v_pk_mul_f32 v[70:71], v[68:69], v[70:71] op_sel_hi:[0,1]
	v_pk_mul_f32 v[72:73], v[68:69], v[84:85] op_sel_hi:[0,1]
	v_pk_fma_f32 v[18:19], v[178:179], v[72:73], v[18:19]
	v_pk_fma_f32 v[16:17], v[176:177], v[70:71], v[16:17]
	v_cvt_pk_bf16_f32 v37, v18, v19
	v_cvt_pk_bf16_f32 v36, v16, v17
	global_store_dwordx2 v[100:101], v[36:37], off offset:2048
	v_mov_b32_e32 v70, v82
	v_mov_b32_e32 v71, v80
	v_mov_b32_e32 v80, v83
	v_pk_mul_f32 v[70:71], v[68:69], v[70:71] op_sel_hi:[0,1]
	v_pk_mul_f32 v[72:73], v[68:69], v[80:81] op_sel_hi:[0,1]
	v_pk_fma_f32 v[14:15], v[182:183], v[72:73], v[14:15]
	v_pk_fma_f32 v[12:13], v[180:181], v[70:71], v[12:13]
	v_cvt_pk_bf16_f32 v37, v14, v15
	v_cvt_pk_bf16_f32 v36, v12, v13
	global_store_dwordx2 v[100:101], v[36:37], off offset:2560
	v_pk_mul_f32 v[70:71], v[68:69], v[76:77] op_sel_hi:[0,1]
	v_pk_mul_f32 v[72:73], v[68:69], v[78:79] op_sel_hi:[0,1]
	v_pk_fma_f32 v[10:11], v[186:187], v[72:73], v[10:11]
	v_pk_fma_f32 v[8:9], v[184:185], v[70:71], v[8:9]
	v_cvt_pk_bf16_f32 v37, v10, v11
	v_cvt_pk_bf16_f32 v36, v8, v9
	global_store_dwordx2 v[100:101], v[36:37], off offset:3072
	v_pk_fma_f32 v[6:7], v[190:191], v[64:65], v[6:7]
	v_pk_fma_f32 v[4:5], v[188:189], v[66:67], v[4:5]
	v_cvt_pk_bf16_f32 v37, v6, v7
	v_cvt_pk_bf16_f32 v36, v4, v5
	v_mov_b32_e32 v38, v33
	v_mov_b32_e32 v39, v29
	global_store_dwordx2 v[100:101], v[36:37], off offset:3584
	v_mov_b32_e32 v36, v32
	v_mov_b32_e32 v37, v28
	v_pk_mul_f32 v[38:39], v[38:39], v[38:39]
	v_mov_b32_e32 v64, v35
	v_mov_b32_e32 v65, v31
	v_pk_fma_f32 v[36:37], v[36:37], v[36:37], v[38:39]
	v_mov_b32_e32 v38, v34
	v_mov_b32_e32 v39, v30
	v_pk_mul_f32 v[64:65], v[64:65], v[64:65]
	s_nop 0
	v_pk_fma_f32 v[38:39], v[38:39], v[38:39], v[64:65]
	v_pk_mul_f32 v[64:65], v[26:27], v[26:27]
	v_pk_add_f32 v[36:37], v[36:37], v[38:39]
	v_pk_mul_f32 v[38:39], v[24:25], v[24:25]
	v_pk_add_f32 v[36:37], v[36:37], v[36:37] op_sel_hi:[0,1]
	v_pk_mov_b32 v[66:67], v[38:39], v[64:65] op_sel:[1,0]
	v_mov_b32_e32 v39, v65
	v_mul_f32_e32 v36, v20, v20
	v_pk_add_f32 v[38:39], v[66:67], v[38:39]
	v_pk_fma_f32 v[64:65], v[20:21], v[20:21], v[36:37] op_sel_hi:[1,1,0]
	v_mul_f32_e32 v36, v22, v22
	v_pk_add_f32 v[38:39], v[38:39], v[38:39] op_sel_hi:[0,1]
	v_pk_fma_f32 v[66:67], v[22:23], v[22:23], v[36:37] op_sel_hi:[1,1,0]
	v_mul_f32_e32 v64, v16, v16
	v_mul_f32_e32 v66, v17, v17
	v_mul_f32_e32 v38, v18, v18
	v_mul_f32_e32 v36, v19, v19
	v_pk_add_f32 v[64:65], v[64:65], v[66:67]
	v_pk_add_f32 v[36:37], v[38:39], v[36:37]
	v_pk_mul_f32 v[38:39], v[12:13], v[12:13]
	v_pk_add_f32 v[36:37], v[64:65], v[36:37]
	v_pk_mul_f32 v[64:65], v[14:15], v[14:15]
	v_pk_add_f32 v[36:37], v[36:37], v[36:37] op_sel_hi:[0,1]
	v_pk_mov_b32 v[66:67], v[38:39], v[64:65] op_sel:[1,0]
	v_mov_b32_e32 v39, v65
	v_mul_f32_e32 v36, v8, v8
	v_pk_add_f32 v[38:39], v[66:67], v[38:39]
	v_pk_fma_f32 v[64:65], v[8:9], v[8:9], v[36:37] op_sel_hi:[1,1,0]
	v_mul_f32_e32 v36, v10, v10
	v_pk_add_f32 v[38:39], v[38:39], v[38:39] op_sel_hi:[0,1]
	v_pk_fma_f32 v[66:67], v[10:11], v[10:11], v[36:37] op_sel_hi:[1,1,0]
	v_mul_f32_e32 v64, v4, v4
	v_mul_f32_e32 v66, v5, v5
	v_mul_f32_e32 v38, v6, v6
	v_mul_f32_e32 v36, v7, v7
	v_pk_add_f32 v[64:65], v[64:65], v[66:67]
	v_pk_add_f32 v[36:37], v[38:39], v[36:37]
	s_nop 0
	v_pk_add_f32 v[36:37], v[64:65], v[36:37]
	v_add_f32_e32 v36, v36, v37
	s_waitcnt lgkmcnt(0)
; __device__ __forceinline__ void row_post1(const Params& p, int layer) {
;     ...
;         const float rs2 = row_rstd(x);
; #pragma unroll
;         for (int j = 0; j < 8; ++j) { const f32x4 g = *(const f32x4*)(g2 + 256 * j + 4 * lane); x[j] = x[j] * rs2 * g; }
;         row_store_bf16((bf16_t*)(ws + WS_HB) + (size_t)m * D, lane, x);
	s_nop 1
	v_add_f32_dpp v36, v36, v36 quad_perm:[1,0,3,2] row_mask:0xf bank_mask:0xf bound_ctrl:1
	s_nop 1
	v_add_f32_dpp v36, v36, v36 quad_perm:[2,3,0,1] row_mask:0xf bank_mask:0xf bound_ctrl:1
	s_nop 1
	v_add_f32_dpp v36, v36, v36 row_half_mirror row_mask:0xf bank_mask:0xf bound_ctrl:1
	s_nop 1
	v_add_f32_dpp v36, v36, v36 row_mirror row_mask:0xf bank_mask:0xf bound_ctrl:1
	s_nop 1
	v_add_f32_dpp v36, v36, v36 row_bcast:15 row_mask:0xa bank_mask:0xf
	s_nop 1
	v_add_f32_dpp v36, v36, v36 row_bcast:31 row_mask:0xc bank_mask:0xf
	s_nop 1
	v_readlane_b32 vcc_lo, v36, 63
	s_nop 2
	v_mov_b32_e32 v36, vcc_lo
	v_fmamk_f32 v36, v36, 0x3a000000, v147
	v_cmp_gt_f32_e32 vcc, s29, v36
	v_mul_f32_e32 v37, 0x4b800000, v36
	s_nop 0
	v_cndmask_b32_e32 v36, v36, v37, vcc
	v_rsq_f32_e32 v36, v36
	s_nop 0
	v_mul_f32_e32 v37, 0x45800000, v36
	v_cndmask_b32_e32 v36, v36, v37, vcc
	v_pk_mul_f32 v[32:33], v[32:33], v[36:37] op_sel_hi:[1,0]
	v_pk_mul_f32 v[34:35], v[34:35], v[36:37] op_sel_hi:[1,0]
	v_pk_mul_f32 v[28:29], v[28:29], v[36:37] op_sel_hi:[1,0]
	v_pk_mul_f32 v[30:31], v[30:31], v[36:37] op_sel_hi:[1,0]
	v_pk_mul_f32 v[24:25], v[24:25], v[36:37] op_sel_hi:[1,0]
	v_pk_mul_f32 v[26:27], v[26:27], v[36:37] op_sel_hi:[1,0]
	v_pk_mul_f32 v[20:21], v[20:21], v[36:37] op_sel_hi:[1,0]
	v_pk_mul_f32 v[22:23], v[22:23], v[36:37] op_sel_hi:[1,0]
	v_pk_mul_f32 v[16:17], v[16:17], v[36:37] op_sel_hi:[1,0]
	v_pk_mul_f32 v[18:19], v[18:19], v[36:37] op_sel_hi:[1,0]
	v_pk_mul_f32 v[12:13], v[12:13], v[36:37] op_sel_hi:[1,0]
	v_pk_mul_f32 v[14:15], v[14:15], v[36:37] op_sel_hi:[1,0]
	v_pk_mul_f32 v[8:9], v[8:9], v[36:37] op_sel_hi:[1,0]
	v_pk_mul_f32 v[10:11], v[10:11], v[36:37] op_sel_hi:[1,0]
	v_pk_mul_f32 v[4:5], v[4:5], v[36:37] op_sel_hi:[1,0]
	v_pk_mul_f32 v[6:7], v[6:7], v[36:37] op_sel_hi:[1,0]
	v_pk_mul_f32 v[38:39], v[194:195], v[34:35]
	v_pk_mul_f32 v[64:65], v[192:193], v[32:33]
	v_pk_mul_f32 v[34:35], v[198:199], v[30:31]
	v_pk_mul_f32 v[32:33], v[196:197], v[28:29]
	v_pk_mul_f32 v[30:31], v[202:203], v[26:27]
	v_pk_mul_f32 v[28:29], v[200:201], v[24:25]
	v_pk_mul_f32 v[26:27], v[206:207], v[22:23]
	v_pk_mul_f32 v[24:25], v[204:205], v[20:21]
	v_pk_mul_f32 v[22:23], v[210:211], v[18:19]
	v_pk_mul_f32 v[20:21], v[208:209], v[16:17]
	v_pk_mul_f32 v[18:19], v[214:215], v[14:15]
	v_pk_mul_f32 v[16:17], v[212:213], v[12:13]
	v_pk_mul_f32 v[14:15], v[218:219], v[10:11]
	v_pk_mul_f32 v[12:13], v[216:217], v[8:9]
	v_pk_mul_f32 v[6:7], v[222:223], v[6:7]
	v_pk_mul_f32 v[4:5], v[220:221], v[4:5]
	v_lshl_add_u64 v[8:9], v[46:47], 0, s[6:7]
	v_cvt_pk_bf16_f32 v10, v64, v65
	v_cvt_pk_bf16_f32 v11, v38, v39
	global_store_dwordx2 v[8:9], v[10:11], off
	v_cvt_pk_bf16_f32 v10, v32, v33
	v_cvt_pk_bf16_f32 v11, v34, v35
	global_store_dwordx2 v[8:9], v[10:11], off offset:512
	v_cvt_pk_bf16_f32 v10, v28, v29
	v_cvt_pk_bf16_f32 v11, v30, v31
	global_store_dwordx2 v[8:9], v[10:11], off offset:1024
	v_cvt_pk_bf16_f32 v10, v24, v25
	v_cvt_pk_bf16_f32 v11, v26, v27
	global_store_dwordx2 v[8:9], v[10:11], off offset:1536
	v_cvt_pk_bf16_f32 v10, v20, v21
	v_cvt_pk_bf16_f32 v11, v22, v23
	global_store_dwordx2 v[8:9], v[10:11], off offset:2048
	v_cvt_pk_bf16_f32 v10, v16, v17
	v_cvt_pk_bf16_f32 v11, v18, v19
	global_store_dwordx2 v[8:9], v[10:11], off offset:2560
	v_cvt_pk_bf16_f32 v10, v12, v13
	v_cvt_pk_bf16_f32 v11, v14, v15
	v_cvt_pk_bf16_f32 v4, v4, v5
	v_cvt_pk_bf16_f32 v5, v6, v7
	s_cselect_b64 s[6:7], -1, 0
	global_store_dwordx2 v[8:9], v[10:11], off offset:3072
	global_store_dwordx2 v[8:9], v[4:5], off offset:3584

; __device__ __forceinline__ void row_load_bf16(const bf16_t* p, int lane, f32x4 (&v)[8]) {
; #pragma unroll
;     for (int j = 0; j < 8; ++j) { const u32x2 r = *(const u32x2*)(p + 256 * j + 4 * lane);
;         v[j][0] = __builtin_bit_cast(float, r.x << 16); v[j][1] = __builtin_bit_cast(float, r.x & 0xffff0000u); v[j][2] = __builtin_bit_cast(float, r.y << 16); v[j][3] = __builtin_bit_cast(float, r.y & 0xffff0000u); }
; __device__ __forceinline__ void row_post1(const Params& p, int layer) {
;     ...
;     for (int it_ = 0; it_ <= nit; ++it_) {
;         int m = gw + it_ * ngw;
;         if (it_ == nit) { if (wave_ >= 4 || bid_ >= MS / 4) break; m = MP + 4 * bid_ + wave_; }
;         f32x4 x[8], mx[8];
;         xrow_load(X, layer == 0, m, lane, x);
;         row_load_bf16(MIX + (size_t)m * D, lane, mx);
.LBB0_989:
	s_cmp_lg_u32 s13, 0
	s_cselect_b64 s[8:9], -1, 0
	s_or_b64 s[6:7], s[8:9], s[2:3]
	s_andn2_b64 vcc, exec, s[6:7]
	s_mov_b64 s[6:7], -1
	s_cbranch_vccnz .LBB0_988
	s_and_b64 s[6:7], s[8:9], exec
	s_cselect_b32 s6, s4, s12
	s_and_b64 vcc, exec, s[40:41]
	s_cbranch_vccz .LBB0_992
	s_ashr_i32 s7, s6, 31
	s_lshl_b64 s[8:9], s[6:7], 12
	v_lshl_add_u64 v[4:5], v[0:1], 0, s[8:9]
	global_load_dwordx2 v[6:7], v[4:5], off
	global_load_dwordx2 v[8:9], v[4:5], off offset:512
	global_load_dwordx2 v[10:11], v[4:5], off offset:1024
	global_load_dwordx2 v[12:13], v[4:5], off offset:1536
	global_load_dwordx2 v[14:15], v[4:5], off offset:2048
	global_load_dwordx2 v[104:105], v[4:5], off offset:2560
	global_load_dwordx2 v[106:107], v[4:5], off offset:3072
	global_load_dwordx2 v[108:109], v[4:5], off offset:3584
	v_lshl_add_u64 v[36:37], v[40:41], 0, s[8:9]
	global_load_dwordx2 v[38:39], v[36:37], off
	global_load_dwordx2 v[76:77], v[36:37], off offset:512
	global_load_dwordx2 v[78:79], v[36:37], off offset:1024
	global_load_dwordx2 v[64:65], v[36:37], off offset:1536
	global_load_dwordx2 v[80:81], v[36:37], off offset:2048
	global_load_dwordx2 v[100:101], v[36:37], off offset:2560
	global_load_dwordx2 v[102:103], v[36:37], off offset:3072
	s_nop 0
	global_load_dwordx2 v[36:37], v[36:37], off offset:3584
	s_mov_b64 s[6:7], s[8:9]
	s_waitcnt vmcnt(15)
	v_lshlrev_b32_e32 v32, 16, v6
	v_and_b32_e32 v33, 0xffff0000, v6
	v_lshlrev_b32_e32 v34, 16, v7
	v_and_b32_e32 v35, 0xffff0000, v7
	s_waitcnt vmcnt(14)
	v_lshlrev_b32_e32 v28, 16, v8
	v_and_b32_e32 v29, 0xffff0000, v8
	v_lshlrev_b32_e32 v30, 16, v9
	v_and_b32_e32 v31, 0xffff0000, v9
	s_waitcnt vmcnt(13)
	v_lshlrev_b32_e32 v24, 16, v10
	v_and_b32_e32 v25, 0xffff0000, v10
	v_lshlrev_b32_e32 v26, 16, v11
	v_and_b32_e32 v27, 0xffff0000, v11
	s_waitcnt vmcnt(12)
	v_lshlrev_b32_e32 v20, 16, v12
	v_and_b32_e32 v21, 0xffff0000, v12
	v_lshlrev_b32_e32 v22, 16, v13
	v_and_b32_e32 v23, 0xffff0000, v13
	s_waitcnt vmcnt(11)
	v_lshlrev_b32_e32 v16, 16, v14
	v_and_b32_e32 v17, 0xffff0000, v14
	v_lshlrev_b32_e32 v18, 16, v15
	v_and_b32_e32 v19, 0xffff0000, v15
	s_waitcnt vmcnt(10)
	v_lshlrev_b32_e32 v12, 16, v104
	v_and_b32_e32 v13, 0xffff0000, v104
	v_lshlrev_b32_e32 v14, 16, v105
	v_and_b32_e32 v15, 0xffff0000, v105
	s_waitcnt vmcnt(9)
	v_lshlrev_b32_e32 v8, 16, v106
	v_and_b32_e32 v9, 0xffff0000, v106
	v_lshlrev_b32_e32 v10, 16, v107
	v_and_b32_e32 v11, 0xffff0000, v107
	s_waitcnt vmcnt(8)
	v_lshlrev_b32_e32 v4, 16, v108
	v_and_b32_e32 v5, 0xffff0000, v108
	v_lshlrev_b32_e32 v6, 16, v109
	v_and_b32_e32 v7, 0xffff0000, v109
	s_branch .Lp1_mixed
